# plus indexer selection: 31 exec-masked individually-waited LDS key reads batched under one exec mask and one wait
# baseline (speedup 1.0000x reference)
; DI int cmp_ge_u(u32 a, u32 b) { int r; asm("v_cmp_ge_u32 vcc, %1, %2\n\tv_cndmask_b32 %0, 0, 1, vcc" : "=v"(r) : "v"(a), "v"(b) : "vcc"); return r; }
; DI int cmp_gt_u(u32 a, u32 b) { int r; asm("v_cmp_gt_u32 vcc, %1, %2\n\tv_cndmask_b32 %0, 0, 1, vcc" : "=v"(r) : "v"(a), "v"(b) : "vcc"); return r; }
; DI int cmp_eq_u(u32 a, u32 b) { int r; asm("v_cmp_eq_u32 vcc, %1, %2\n\tv_cndmask_b32 %0, 0, 1, vcc" : "=v"(r) : "v"(a), "v"(b) : "vcc"); return r; }
; DI void indexer_phase(const Params& p, unsigned char* smem) {
;     ...
;       u32 wv2[32];
;       const bool lane_ok = (lane < 2 * nw);
;       int gtc = 0, eqc = 0;
; #pragma unroll
;       for (int jj = 0; jj < 32; ++jj) {
;         u32 val = lane_ok ? row[33 * lane + jj] : 0u;
;         wv2[jj] = val;
;         gtc += cmp_gt_u(val, Tt);
;         eqc += cmp_eq_u(val, Tt);
;       }
.LBB0_1117:
	s_xor_b64 s[28:29], s[96:97], -1
	s_waitcnt lgkmcnt(2)
	v_mov_b32_e32 v0, 0
	v_add_u32_e32 v18, v25, v131
	v_mov_b32_e32 v1, 0
	v_mov_b32_e32 v1, 0
	v_mov_b32_e32 v0, 0
	v_mov_b32_e32 v3, 0
	v_mov_b32_e32 v2, 0
	v_mov_b32_e32 v5, 0
	v_mov_b32_e32 v4, 0
	v_mov_b32_e32 v7, 0
	v_mov_b32_e32 v6, 0
	v_mov_b32_e32 v10, 0
	v_mov_b32_e32 v9, 0
	v_mov_b32_e32 v12, 0
	v_mov_b32_e32 v11, 0
	v_mov_b32_e32 v14, 0
	v_mov_b32_e32 v13, 0
	v_mov_b32_e32 v16, 0
	v_mov_b32_e32 v15, 0
	v_mov_b32_e32 v19, 0
	v_mov_b32_e32 v17, 0
	v_mov_b32_e32 v23, 0
	v_mov_b32_e32 v22, 0
	v_mov_b32_e32 v28, 0
	v_mov_b32_e32 v27, 0
	v_mov_b32_e32 v32, 0
	v_mov_b32_e32 v31, 0
	v_mov_b32_e32 v38, 0
	v_mov_b32_e32 v35, 0
	v_mov_b32_e32 v42, 0
	v_mov_b32_e32 v39, 0
	v_mov_b32_e32 v46, 0
	v_mov_b32_e32 v43, 0
	v_mov_b32_e32 v49, 0
	s_and_saveexec_b64 s[96:97], s[20:21]
	ds_read_b32 v1, v18
	ds_read_b32 v0, v18 offset:4
	ds_read_b32 v3, v18 offset:8
	ds_read_b32 v2, v18 offset:12
	ds_read_b32 v5, v18 offset:16
	ds_read_b32 v4, v18 offset:20
	ds_read_b32 v7, v18 offset:24
	ds_read_b32 v6, v18 offset:28
	ds_read_b32 v10, v18 offset:32
	ds_read_b32 v9, v18 offset:36
	ds_read_b32 v12, v18 offset:40
	ds_read_b32 v11, v18 offset:44
	ds_read_b32 v14, v18 offset:48
	ds_read_b32 v13, v18 offset:52
	ds_read_b32 v16, v18 offset:56
	ds_read_b32 v15, v18 offset:60
	ds_read_b32 v19, v18 offset:64
	ds_read_b32 v17, v18 offset:68
	ds_read_b32 v23, v18 offset:72
	ds_read_b32 v22, v18 offset:76
	ds_read_b32 v28, v18 offset:80
	ds_read_b32 v27, v18 offset:84
	ds_read_b32 v32, v18 offset:88
	ds_read_b32 v31, v18 offset:92
	ds_read_b32 v38, v18 offset:96
	ds_read_b32 v35, v18 offset:100
	ds_read_b32 v42, v18 offset:104
	ds_read_b32 v39, v18 offset:108
	ds_read_b32 v46, v18 offset:112
	ds_read_b32 v43, v18 offset:116
	ds_read_b32 v49, v18 offset:120
	s_or_b64 exec, exec, s[96:97]
	s_waitcnt lgkmcnt(0)
	s_waitcnt lgkmcnt(0)
	v_cmp_gt_u32 vcc, v1, v8
	v_cndmask_b32 v20, 0, 1, vcc
	s_nop 0
	v_cmp_eq_u32 vcc, v1, v8
	v_cndmask_b32 v21, 0, 1, vcc
	s_waitcnt lgkmcnt(0)
	v_cmp_gt_u32 vcc, v0, v8
	v_cndmask_b32 v25, 0, 1, vcc
	s_nop 0
	v_cmp_eq_u32 vcc, v0, v8
	v_cndmask_b32 v26, 0, 1, vcc
	s_waitcnt lgkmcnt(0)
	v_cmp_gt_u32 vcc, v3, v8
	v_cndmask_b32 v29, 0, 1, vcc
	s_nop 0
	v_cmp_eq_u32 vcc, v3, v8
	v_cndmask_b32 v30, 0, 1, vcc
	s_waitcnt lgkmcnt(0)
	v_cmp_gt_u32 vcc, v2, v8
	v_cndmask_b32 v33, 0, 1, vcc
	s_nop 0
	v_cmp_eq_u32 vcc, v2, v8
	v_cndmask_b32 v34, 0, 1, vcc
	s_waitcnt lgkmcnt(0)
	v_cmp_gt_u32 vcc, v5, v8
	v_cndmask_b32 v36, 0, 1, vcc
	s_nop 0
	v_cmp_eq_u32 vcc, v5, v8
	v_cndmask_b32 v37, 0, 1, vcc
	s_waitcnt lgkmcnt(0)
	v_cmp_gt_u32 vcc, v4, v8
	v_cndmask_b32 v40, 0, 1, vcc
	s_nop 0
	v_cmp_eq_u32 vcc, v4, v8
	v_cndmask_b32 v41, 0, 1, vcc
	s_waitcnt lgkmcnt(0)
	v_cmp_gt_u32 vcc, v7, v8
	v_cndmask_b32 v44, 0, 1, vcc
	s_nop 0
	v_cmp_eq_u32 vcc, v7, v8
	v_cndmask_b32 v45, 0, 1, vcc
	s_waitcnt lgkmcnt(0)
	v_cmp_gt_u32 vcc, v6, v8
	v_cndmask_b32 v47, 0, 1, vcc
	s_nop 0
	v_cmp_eq_u32 vcc, v6, v8
	v_cndmask_b32 v48, 0, 1, vcc
	s_waitcnt lgkmcnt(0)
	v_cmp_gt_u32 vcc, v10, v8
	v_cndmask_b32 v50, 0, 1, vcc
	s_nop 0
	v_cmp_eq_u32 vcc, v10, v8
	v_cndmask_b32 v51, 0, 1, vcc
	s_waitcnt lgkmcnt(0)
	v_cmp_gt_u32 vcc, v9, v8
	v_cndmask_b32 v52, 0, 1, vcc
	s_nop 0
	v_cmp_eq_u32 vcc, v9, v8
	v_cndmask_b32 v53, 0, 1, vcc
	s_waitcnt lgkmcnt(0)
	v_cmp_gt_u32 vcc, v12, v8
	v_cndmask_b32 v54, 0, 1, vcc
	s_nop 0
	v_cmp_eq_u32 vcc, v12, v8
	v_cndmask_b32 v55, 0, 1, vcc
	s_waitcnt lgkmcnt(0)
	v_cmp_gt_u32 vcc, v11, v8
	v_cndmask_b32 v56, 0, 1, vcc
	s_nop 0
	v_cmp_eq_u32 vcc, v11, v8
	v_cndmask_b32 v57, 0, 1, vcc
	s_waitcnt lgkmcnt(0)
	v_cmp_gt_u32 vcc, v14, v8
	v_cndmask_b32 v58, 0, 1, vcc
	s_nop 0
	v_cmp_eq_u32 vcc, v14, v8
	v_cndmask_b32 v59, 0, 1, vcc
	s_waitcnt lgkmcnt(0)
	v_cmp_gt_u32 vcc, v13, v8
	v_cndmask_b32 v60, 0, 1, vcc
	s_nop 0
	v_cmp_eq_u32 vcc, v13, v8
	v_cndmask_b32 v61, 0, 1, vcc
	s_waitcnt lgkmcnt(0)
	v_cmp_gt_u32 vcc, v16, v8
	v_cndmask_b32 v62, 0, 1, vcc
	s_nop 0
	v_cmp_eq_u32 vcc, v16, v8
	v_cndmask_b32 v63, 0, 1, vcc
	s_waitcnt lgkmcnt(0)
	v_cmp_gt_u32 vcc, v15, v8
	v_cndmask_b32 v64, 0, 1, vcc
	s_nop 0
	v_cmp_eq_u32 vcc, v15, v8
	v_cndmask_b32 v65, 0, 1, vcc
	s_waitcnt lgkmcnt(0)
	v_cmp_gt_u32 vcc, v19, v8
	v_cndmask_b32 v66, 0, 1, vcc
	s_nop 0
	v_cmp_eq_u32 vcc, v19, v8
	v_cndmask_b32 v67, 0, 1, vcc
	s_waitcnt lgkmcnt(0)
	v_cmp_gt_u32 vcc, v17, v8
	v_cndmask_b32 v69, 0, 1, vcc
	s_nop 0
	v_cmp_eq_u32 vcc, v17, v8
	v_cndmask_b32 v70, 0, 1, vcc
	s_waitcnt lgkmcnt(0)
	v_cmp_gt_u32 vcc, v23, v8
	v_cndmask_b32 v72, 0, 1, vcc
	s_nop 0
	v_cmp_eq_u32 vcc, v23, v8
	v_cndmask_b32 v68, 0, 1, vcc
	s_waitcnt lgkmcnt(0)
	v_cmp_gt_u32 vcc, v22, v8
	v_cndmask_b32 v74, 0, 1, vcc
	s_nop 0
	v_cmp_eq_u32 vcc, v22, v8
	v_cndmask_b32 v71, 0, 1, vcc
	s_waitcnt lgkmcnt(0)
	v_cmp_gt_u32 vcc, v28, v8
	v_cndmask_b32 v76, 0, 1, vcc
	s_nop 0
	v_cmp_eq_u32 vcc, v28, v8
	v_cndmask_b32 v73, 0, 1, vcc
	s_waitcnt lgkmcnt(0)
	v_cmp_gt_u32 vcc, v27, v8
	v_cndmask_b32 v78, 0, 1, vcc
	s_nop 0
	v_cmp_eq_u32 vcc, v27, v8
	v_cndmask_b32 v75, 0, 1, vcc
	s_waitcnt lgkmcnt(0)
	v_cmp_gt_u32 vcc, v32, v8
	v_cndmask_b32 v80, 0, 1, vcc
	s_nop 0
	v_cmp_eq_u32 vcc, v32, v8
	v_cndmask_b32 v77, 0, 1, vcc
	s_waitcnt lgkmcnt(0)
	v_cmp_gt_u32 vcc, v31, v8
	v_cndmask_b32 v82, 0, 1, vcc
	s_nop 0
	v_cmp_eq_u32 vcc, v31, v8
	v_cndmask_b32 v79, 0, 1, vcc
	s_waitcnt lgkmcnt(0)
	v_cmp_gt_u32 vcc, v38, v8
	v_cndmask_b32 v84, 0, 1, vcc
	s_nop 0
	v_cmp_eq_u32 vcc, v38, v8
	v_cndmask_b32 v81, 0, 1, vcc
	s_waitcnt lgkmcnt(0)
	v_cmp_gt_u32 vcc, v35, v8
	v_cndmask_b32 v86, 0, 1, vcc
	s_nop 0
	v_cmp_eq_u32 vcc, v35, v8
	v_cndmask_b32 v83, 0, 1, vcc
	s_waitcnt lgkmcnt(0)
	v_cmp_gt_u32 vcc, v42, v8
	v_cndmask_b32 v88, 0, 1, vcc
	s_nop 0
	v_cmp_eq_u32 vcc, v42, v8
	v_cndmask_b32 v85, 0, 1, vcc
	s_waitcnt lgkmcnt(0)
	v_cmp_gt_u32 vcc, v39, v8
	v_cndmask_b32 v90, 0, 1, vcc
	s_nop 0
	v_cmp_eq_u32 vcc, v39, v8
	v_cndmask_b32 v87, 0, 1, vcc
	s_waitcnt lgkmcnt(0)
	v_cmp_gt_u32 vcc, v46, v8
	v_cndmask_b32 v93, 0, 1, vcc
	s_nop 0
	v_cmp_eq_u32 vcc, v46, v8
	v_cndmask_b32 v89, 0, 1, vcc
	v_mov_b32_e32 v92, 0
	s_waitcnt lgkmcnt(0)
	v_cmp_gt_u32 vcc, v43, v8
	v_cndmask_b32 v95, 0, 1, vcc
	s_nop 0
	v_cmp_eq_u32 vcc, v43, v8
	v_cndmask_b32 v91, 0, 1, vcc
	s_waitcnt lgkmcnt(0)
	v_cmp_gt_u32 vcc, v49, v8
	v_cndmask_b32 v96, 0, 1, vcc
	s_nop 0
	v_cmp_eq_u32 vcc, v49, v8
	v_cndmask_b32 v94, 0, 1, vcc
	s_and_saveexec_b64 s[96:97], s[20:21]
	s_cbranch_execz .LBB0_1071
	ds_read_b32 v92, v18 offset:124
	s_branch .LBB0_1071
